# baseline (speedup 1.0000x reference)
; template <int DQK, int MODE> ...
;     ...
;   auto lstore = [&](const TRegs& R, int st) {
;     u16* Ks = lds + st * STG;
;     u16* Vs = Ks + KT;
; #pragma unroll
;     for (int i = 0; i < NKL; ++i) {
;       int c = tid + i * 256;
;       int row = c / KCH, cc = c % KCH;
;       *(u32x4*)(Ks + row * KST + cc * 8) = R.k[i];
;     }
; #pragma unroll
;     for (int i = 0; i < 2; ++i) {
;       int c = tid + i * 256;
;       int d = c >> 3, cc = c & 7;
;       u32x2 lo = {R.v[i].x, R.v[i].y}, hi = {R.v[i].z, R.v[i].w};
;       *(u32x2*)(Vs + d * VST + cc * 8) = lo;
;       *(u32x2*)(Vs + d * VST + cc * 8 + 4) = hi;
;     }
;   };
;     ...
;       {
;         bf16x8 kf[2][NKK];
; #pragma unroll
;         for (int ku = 0; ku < 2; ++ku)
; #pragma unroll
;           for (int kk = 0; kk < NKK; ++kk)
;             kf[ku][kk] = *(const bf16x8*)(Ks + (ku * 32 + ql) * KST + kk * 16 + hh * 8);
;         __builtin_amdgcn_sched_barrier(0);
; #pragma unroll
;         for (int ku = 0; ku < 2; ++ku)
; #pragma unroll
;           for (int r = 0; r < 16; ++r) S[ku][r] = cinit;
; #pragma unroll
;         for (int kk = 0; kk < NKK; ++kk)
; #pragma unroll
;           for (int ku = 0; ku < 2; ++ku)
;             S[ku] = __builtin_amdgcn_mfma_f32_32x32x16_bf16(kf[ku][kk], qf[kk], S[ku], 0, 0, 0);
;       }
.LBB0_992:
	s_and_saveexec_b64 s[16:17], s[18:19]
	s_cbranch_execz .Lmy_ia0_a
	ds_read_b128 v[4:7], v185
	ds_read_b128 v[158:161], v185 offset:6656
	ds_read_b128 v[8:11], v185 offset:32
	ds_read_b128 v[162:165], v185 offset:6688
	ds_read_b128 v[12:15], v185 offset:64
	ds_read_b128 v[204:207], v185 offset:6720
	ds_read_b128 v[146:149], v185 offset:96
	ds_read_b128 v[208:211], v185 offset:6752
	ds_read_b128 v[150:153], v185 offset:128
	ds_read_b128 v[212:215], v185 offset:6784
	ds_read_b128 v[154:157], v185 offset:160
	ds_read_b128 v[216:219], v185 offset:6816
	s_waitcnt lgkmcnt(11)
	v_mfma_f32_32x32x16_bf16 v[66:81], v[4:7], v[86:89], v[228:243]
	v_add_u32_e32 v4, 0x3000, v187
	s_waitcnt lgkmcnt(10)
	v_mfma_f32_32x32x16_bf16 v[50:65], v[158:161], v[86:89], v[228:243]
	s_waitcnt lgkmcnt(9)
	v_mfma_f32_32x32x16_bf16 v[66:81], v[8:11], v[82:85], v[66:81]
	s_waitcnt lgkmcnt(8)
	v_mfma_f32_32x32x16_bf16 v[50:65], v[162:165], v[82:85], v[50:65]
	ds_read2_b64 v[162:165], v4 offset0:128 offset1:130
	s_waitcnt lgkmcnt(8)
	v_mfma_f32_32x32x16_bf16 v[66:81], v[12:15], v[94:97], v[66:81]
	s_waitcnt lgkmcnt(7)
	v_mfma_f32_32x32x16_bf16 v[50:65], v[204:207], v[94:97], v[50:65]
	s_cmp_gt_i32 s5, s2
	s_cbranch_scc1 .Lmy_w1_nl
	v_add_u32_e32 v226, 0x8e00, v184
	s_waitcnt vmcnt(9)
	ds_write_b128 v201, v[122:125] offset:23040
	s_waitcnt vmcnt(8)
	ds_write_b128 v202, v[126:129] offset:23040
	s_waitcnt vmcnt(7)
	ds_write_b128 v203, v[134:137] offset:23040
	s_waitcnt vmcnt(6)
	ds_write2_b64 v226, v[138:139], v[140:141] offset1:1
	v_add_u32_e32 v226, 0x8e00, v186
	s_waitcnt vmcnt(5)
	ds_write2_b64 v226, v[142:143], v[144:145] offset1:1
	s_branch .Lmy_w1_dn

; template <int DQK, int MODE> ...
;     ...
;         for (int kk = 0; kk < NKK; ++kk)
; #pragma unroll
;           for (int ku = 0; ku < 2; ++ku)
;             S[ku] = __builtin_amdgcn_mfma_f32_32x32x16_bf16(kf[ku][kk], qf[kk], S[ku], 0, 0, 0);
;       }
;       u32x4 vf[2][4];
;       if (MODE != 2) {
; #pragma unroll
;         for (int du = 0; du < 2; ++du)
; #pragma unroll
;           for (int s4 = 0; s4 < 4; ++s4) {
;             const u16* vp = Vs + (du * 32 + ql) * VST + 16 * s4 + 4 * hh;
;             u32x2 a = *(const u32x2*)vp;
;             u32x2 b = *(const u32x2*)(vp + 8);
;             vf[du][s4] = (u32x4){a.x, a.y, b.x, b.y};
;           }
;         __builtin_amdgcn_sched_barrier(0);
;       }
;       bf16x8 pf[4];
;       if (MODE != 2) {
;         if (MODE == 1 && !far) {
;           const bool noclip = ((qpos0 + 32 * w + 31) - j * 64 <= 256) && ((qpos0 + 32 * w) - (j * 64 + 63) >= -256);
;           if (noclip) {
;             const float* bt = btab + 256 + qpos - j * 64;
; #pragma unroll
;             for (int ku = 0; ku < 2; ++ku)
; #pragma unroll
;               for (int r = 0; r < 16; ++r) S[ku][r] += bt[-(32 * ku + (r & 3) + 8 * (r >> 2) + 4 * hh)];
;           } else {
; #pragma unroll
;             for (int ku = 0; ku < 2; ++ku)
; #pragma unroll
;               for (int r = 0; r < 16; ++r) {
;                 int key = 32 * ku + (r & 3) + 8 * (r >> 2) + 4 * hh;
;                 int rel = qpos - (j * 64 + key);
;                 rel = min(256, max(-256, rel)) + 256;
;                 S[ku][r] += btab[rel];
;               }
;           }
;         }
;         float mx = -1e30f;
; #pragma unroll
;         for (int ku = 0; ku < 2; ++ku)
; #pragma unroll
;           for (int r = 0; r < 16; ++r) mx = fmaxf(mx, S[ku][r]);
;         if (__builtin_amdgcn_ballot_w64(first || mx > 6.f) != 0ull) {
;           mx = xhalf_max(mx);
;           const float d = first ? mx : (mx > 6.f ? mx : 0.f);
;           const float alpha = first ? 1.f : __builtin_amdgcn_exp2f(-d);
;           m_run += d;
;           lsum *= alpha;
; #pragma unroll
;           for (int ku = 0; ku < 2; ++ku)
; #pragma unroll
;             for (int r = 0; r < 16; ++r) S[ku][r] -= d;
; #pragma unroll
;           for (int du = 0; du < 2; ++du)
; #pragma unroll
;             for (int r = 0; r < 16; ++r) O[du][r] *= alpha;
;         }
.Lmy_w1_dn:
	s_waitcnt lgkmcnt(11)
	v_mfma_f32_32x32x16_bf16 v[66:81], v[146:149], v[90:93], v[66:81]
	s_waitcnt lgkmcnt(10)
	v_mfma_f32_32x32x16_bf16 v[50:65], v[208:211], v[90:93], v[50:65]
	s_waitcnt lgkmcnt(9)
	v_mfma_f32_32x32x16_bf16 v[66:81], v[150:153], v[102:105], v[66:81]
	s_waitcnt lgkmcnt(8)
	v_mfma_f32_32x32x16_bf16 v[50:65], v[212:215], v[102:105], v[50:65]
	s_waitcnt lgkmcnt(7)
	v_mfma_f32_32x32x16_bf16 v[66:81], v[154:157], v[98:101], v[66:81]
	ds_read2_b64 v[154:157], v4 offset0:132 offset1:134
	ds_read2_b64 v[146:149], v4 offset0:136 offset1:138
	ds_read2_b64 v[8:11], v4 offset0:140 offset1:142
	v_add_u32_e32 v4, 0x4000, v187
	ds_read2_b64 v[158:161], v4 offset0:224 offset1:226
	ds_read2_b64 v[150:153], v4 offset0:228 offset1:230
	ds_read2_b64 v[12:15], v4 offset0:232 offset1:234
	ds_read2_b64 v[4:7], v4 offset0:236 offset1:238
	s_waitcnt lgkmcnt(13)
	v_mfma_f32_32x32x16_bf16 v[50:65], v[216:219], v[98:101], v[50:65]
	s_nop 1
	v_max3_f32 v16, v66, s38, v67
	v_max3_f32 v16, v16, v68, v69
	v_max3_f32 v16, v16, v70, v71
	v_max3_f32 v16, v16, v72, v73
	v_max3_f32 v16, v16, v74, v75
	v_max3_f32 v16, v16, v76, v77
	v_max3_f32 v16, v16, v78, v79
	v_max3_f32 v16, v16, v80, v81
	s_nop 1
	v_max3_f32 v16, v16, v50, v51
	v_max3_f32 v16, v16, v52, v53
	v_max3_f32 v16, v16, v54, v55
	v_max3_f32 v16, v16, v56, v57
	v_max3_f32 v16, v16, v58, v59
	v_max3_f32 v16, v16, v60, v61
	v_max3_f32 v16, v16, v62, v63
	v_max3_f32 v16, v16, v64, v65
	v_cmp_lt_f32_e32 vcc, s39, v16
	s_or_b64 vcc, s[0:1], vcc
	s_cbranch_vccz .LBB0_995
	v_mov_b32_e32 v17, v16
	s_nop 1
	v_permlane32_swap_b32_e32 v16, v17
	v_max_f32_e32 v17, v17, v17
	v_max_f32_e32 v16, v16, v16
	v_max_f32_e32 v16, v16, v17
	v_cmp_lt_f32_e32 vcc, s39, v16
	s_or_b64 vcc, s[0:1], vcc
	s_nop 0
	v_cndmask_b32_e32 v16, 0, v16, vcc
	v_exp_f32_e64 v17, -v16
	v_add_f32_e32 v2, v2, v16
	v_sub_f32_e32 v228, 0, v2
	v_mov_b32_e32 v229, v228
	v_mov_b32_e32 v230, v228
	v_mov_b32_e32 v231, v228
	v_mov_b32_e32 v232, v228
	v_mov_b32_e32 v233, v228
	v_mov_b32_e32 v234, v228
	v_mov_b32_e32 v235, v228
	v_mov_b32_e32 v236, v228
	v_mov_b32_e32 v237, v228
	v_mov_b32_e32 v238, v228
	v_mov_b32_e32 v239, v228
	v_mov_b32_e32 v240, v228
	v_mov_b32_e32 v241, v228
	v_mov_b32_e32 v242, v228
	v_mov_b32_e32 v243, v228
	v_cndmask_b32_e64 v204, v17, 1.0, s[0:1]
	v_mul_f32_e32 v177, v177, v204
	v_pk_add_f32 v[66:67], v[66:67], v[16:17] op_sel_hi:[1,0] neg_lo:[0,1] neg_hi:[0,1]
	v_pk_add_f32 v[68:69], v[68:69], v[16:17] op_sel_hi:[1,0] neg_lo:[0,1] neg_hi:[0,1]
	v_pk_add_f32 v[70:71], v[70:71], v[16:17] op_sel_hi:[1,0] neg_lo:[0,1] neg_hi:[0,1]
	v_pk_add_f32 v[72:73], v[72:73], v[16:17] op_sel_hi:[1,0] neg_lo:[0,1] neg_hi:[0,1]
	v_pk_add_f32 v[74:75], v[74:75], v[16:17] op_sel_hi:[1,0] neg_lo:[0,1] neg_hi:[0,1]
	v_pk_add_f32 v[76:77], v[76:77], v[16:17] op_sel_hi:[1,0] neg_lo:[0,1] neg_hi:[0,1]
	v_pk_add_f32 v[78:79], v[78:79], v[16:17] op_sel_hi:[1,0] neg_lo:[0,1] neg_hi:[0,1]
	v_pk_add_f32 v[80:81], v[80:81], v[16:17] op_sel_hi:[1,0] neg_lo:[0,1] neg_hi:[0,1]
	v_pk_add_f32 v[50:51], v[50:51], v[16:17] op_sel_hi:[1,0] neg_lo:[0,1] neg_hi:[0,1]
	v_pk_add_f32 v[52:53], v[52:53], v[16:17] op_sel_hi:[1,0] neg_lo:[0,1] neg_hi:[0,1]
	v_pk_add_f32 v[54:55], v[54:55], v[16:17] op_sel_hi:[1,0] neg_lo:[0,1] neg_hi:[0,1]
	v_pk_add_f32 v[56:57], v[56:57], v[16:17] op_sel_hi:[1,0] neg_lo:[0,1] neg_hi:[0,1]
	v_pk_add_f32 v[58:59], v[58:59], v[16:17] op_sel_hi:[1,0] neg_lo:[0,1] neg_hi:[0,1]
	v_pk_add_f32 v[60:61], v[60:61], v[16:17] op_sel_hi:[1,0] neg_lo:[0,1] neg_hi:[0,1]
	v_pk_add_f32 v[62:63], v[62:63], v[16:17] op_sel_hi:[1,0] neg_lo:[0,1] neg_hi:[0,1]
	v_pk_add_f32 v[64:65], v[64:65], v[16:17] op_sel_hi:[1,0] neg_lo:[0,1] neg_hi:[0,1]
	v_pk_mul_f32 v[48:49], v[48:49], v[204:205] op_sel_hi:[1,0]
	v_pk_mul_f32 v[46:47], v[46:47], v[204:205] op_sel_hi:[1,0]
	v_pk_mul_f32 v[44:45], v[44:45], v[204:205] op_sel_hi:[1,0]
	v_pk_mul_f32 v[42:43], v[42:43], v[204:205] op_sel_hi:[1,0]
	v_pk_mul_f32 v[40:41], v[40:41], v[204:205] op_sel_hi:[1,0]
	v_pk_mul_f32 v[38:39], v[38:39], v[204:205] op_sel_hi:[1,0]
	v_pk_mul_f32 v[36:37], v[36:37], v[204:205] op_sel_hi:[1,0]
	v_pk_mul_f32 v[34:35], v[34:35], v[204:205] op_sel_hi:[1,0]
	v_pk_mul_f32 v[32:33], v[32:33], v[204:205] op_sel_hi:[1,0]
	v_pk_mul_f32 v[30:31], v[30:31], v[204:205] op_sel_hi:[1,0]
	v_pk_mul_f32 v[28:29], v[28:29], v[204:205] op_sel_hi:[1,0]
	v_pk_mul_f32 v[26:27], v[26:27], v[204:205] op_sel_hi:[1,0]
	v_pk_mul_f32 v[24:25], v[24:25], v[204:205] op_sel_hi:[1,0]
	v_pk_mul_f32 v[22:23], v[22:23], v[204:205] op_sel_hi:[1,0]
	v_pk_mul_f32 v[20:21], v[20:21], v[204:205] op_sel_hi:[1,0]
	v_pk_mul_f32 v[18:19], v[18:19], v[204:205] op_sel_hi:[1,0]

; template <int DQK, int MODE> ...
;     ...
;   auto lstore = [&](const TRegs& R, int st) {
;     u16* Ks = lds + st * STG;
;     u16* Vs = Ks + KT;
; #pragma unroll
;     for (int i = 0; i < NKL; ++i) {
;       int c = tid + i * 256;
;       int row = c / KCH, cc = c % KCH;
;       *(u32x4*)(Ks + row * KST + cc * 8) = R.k[i];
;     }
; #pragma unroll
;     for (int i = 0; i < 2; ++i) {
;       int c = tid + i * 256;
;       int d = c >> 3, cc = c & 7;
;       u32x2 lo = {R.v[i].x, R.v[i].y}, hi = {R.v[i].z, R.v[i].w};
;       *(u32x2*)(Vs + d * VST + cc * 8) = lo;
;       *(u32x2*)(Vs + d * VST + cc * 8 + 4) = hi;
;     }
;   };
;     ...
;       {
;         bf16x8 kf[2][NKK];
; #pragma unroll
;         for (int ku = 0; ku < 2; ++ku)
; #pragma unroll
;           for (int kk = 0; kk < NKK; ++kk)
;             kf[ku][kk] = *(const bf16x8*)(Ks + (ku * 32 + ql) * KST + kk * 16 + hh * 8);
;         __builtin_amdgcn_sched_barrier(0);
; #pragma unroll
;         for (int ku = 0; ku < 2; ++ku)
; #pragma unroll
;           for (int r = 0; r < 16; ++r) S[ku][r] = cinit;
; #pragma unroll
;         for (int kk = 0; kk < NKK; ++kk)
; #pragma unroll
;           for (int ku = 0; ku < 2; ++ku)
;             S[ku] = __builtin_amdgcn_mfma_f32_32x32x16_bf16(kf[ku][kk], qf[kk], S[ku], 0, 0, 0);
;       }
.LBB0_999:
	s_and_saveexec_b64 s[16:17], s[6:7]
	s_cbranch_execz .Lmy_ia1_a
	ds_read_b128 v[4:7], v185 offset:23040
	ds_read_b128 v[158:161], v185 offset:29696
	ds_read_b128 v[8:11], v185 offset:23072
	ds_read_b128 v[162:165], v185 offset:29728
	ds_read_b128 v[12:15], v185 offset:23104
	ds_read_b128 v[204:207], v185 offset:29760
	ds_read_b128 v[146:149], v185 offset:23136
	ds_read_b128 v[208:211], v185 offset:29792
	ds_read_b128 v[150:153], v185 offset:23168
	ds_read_b128 v[212:215], v185 offset:29824
	ds_read_b128 v[154:157], v185 offset:23200
	ds_read_b128 v[216:219], v185 offset:29856
	s_waitcnt lgkmcnt(11)
	v_mfma_f32_32x32x16_bf16 v[66:81], v[4:7], v[86:89], v[228:243]
	v_add_u32_e32 v4, 0x8800, v187
	s_waitcnt lgkmcnt(10)
	v_mfma_f32_32x32x16_bf16 v[50:65], v[158:161], v[86:89], v[228:243]
	s_waitcnt lgkmcnt(9)
	v_mfma_f32_32x32x16_bf16 v[66:81], v[8:11], v[82:85], v[66:81]
	s_waitcnt lgkmcnt(8)
	v_mfma_f32_32x32x16_bf16 v[50:65], v[162:165], v[82:85], v[50:65]
	ds_read2_b64 v[162:165], v4 offset0:192 offset1:194
	s_waitcnt lgkmcnt(8)
	v_mfma_f32_32x32x16_bf16 v[66:81], v[12:15], v[94:97], v[66:81]
	s_waitcnt lgkmcnt(7)
	v_mfma_f32_32x32x16_bf16 v[50:65], v[204:207], v[94:97], v[50:65]
	s_cmp_gt_i32 s3, s2
	s_cbranch_scc1 .Lmy_w2_nl
	v_add_u32_e32 v226, 0x3400, v184
	s_waitcnt vmcnt(9)
	ds_write_b128 v201, v[106:109]
	s_waitcnt vmcnt(8)
	ds_write_b128 v202, v[110:113]
	s_waitcnt vmcnt(7)
	ds_write_b128 v203, v[114:117]
	s_waitcnt vmcnt(6)
	ds_write2_b64 v226, v[118:119], v[120:121] offset1:1
	v_add_u32_e32 v226, 0x3400, v186
	s_waitcnt vmcnt(5)
	ds_write2_b64 v226, v[130:131], v[132:133] offset1:1
	s_branch .Lmy_w2_dn

; template <int DQK, int MODE> ...
;     ...
;         for (int kk = 0; kk < NKK; ++kk)
; #pragma unroll
;           for (int ku = 0; ku < 2; ++ku)
;             S[ku] = __builtin_amdgcn_mfma_f32_32x32x16_bf16(kf[ku][kk], qf[kk], S[ku], 0, 0, 0);
;       }
;       u32x4 vf[2][4];
;       if (MODE != 2) {
; #pragma unroll
;         for (int du = 0; du < 2; ++du)
; #pragma unroll
;           for (int s4 = 0; s4 < 4; ++s4) {
;             const u16* vp = Vs + (du * 32 + ql) * VST + 16 * s4 + 4 * hh;
;             u32x2 a = *(const u32x2*)vp;
;             u32x2 b = *(const u32x2*)(vp + 8);
;             vf[du][s4] = (u32x4){a.x, a.y, b.x, b.y};
;           }
;         __builtin_amdgcn_sched_barrier(0);
;       }
;       bf16x8 pf[4];
;       if (MODE != 2) {
;         if (MODE == 1 && !far) {
;           const bool noclip = ((qpos0 + 32 * w + 31) - j * 64 <= 256) && ((qpos0 + 32 * w) - (j * 64 + 63) >= -256);
;           if (noclip) {
;             const float* bt = btab + 256 + qpos - j * 64;
; #pragma unroll
;             for (int ku = 0; ku < 2; ++ku)
; #pragma unroll
;               for (int r = 0; r < 16; ++r) S[ku][r] += bt[-(32 * ku + (r & 3) + 8 * (r >> 2) + 4 * hh)];
;           } else {
; #pragma unroll
;             for (int ku = 0; ku < 2; ++ku)
; #pragma unroll
;               for (int r = 0; r < 16; ++r) {
;                 int key = 32 * ku + (r & 3) + 8 * (r >> 2) + 4 * hh;
;                 int rel = qpos - (j * 64 + key);
;                 rel = min(256, max(-256, rel)) + 256;
;                 S[ku][r] += btab[rel];
;               }
;           }
;         }
;         float mx = -1e30f;
; #pragma unroll
;         for (int ku = 0; ku < 2; ++ku)
; #pragma unroll
;           for (int r = 0; r < 16; ++r) mx = fmaxf(mx, S[ku][r]);
;         if (__builtin_amdgcn_ballot_w64(first || mx > 6.f) != 0ull) {
;           mx = xhalf_max(mx);
;           const float d = first ? mx : (mx > 6.f ? mx : 0.f);
;           const float alpha = first ? 1.f : __builtin_amdgcn_exp2f(-d);
;           m_run += d;
;           lsum *= alpha;
; #pragma unroll
;           for (int ku = 0; ku < 2; ++ku)
; #pragma unroll
;             for (int r = 0; r < 16; ++r) S[ku][r] -= d;
; #pragma unroll
;           for (int du = 0; du < 2; ++du)
; #pragma unroll
;             for (int r = 0; r < 16; ++r) O[du][r] *= alpha;
;         }
.Lmy_w2_dn:
	s_waitcnt lgkmcnt(11)
	v_mfma_f32_32x32x16_bf16 v[66:81], v[146:149], v[90:93], v[66:81]
	s_waitcnt lgkmcnt(10)
	v_mfma_f32_32x32x16_bf16 v[50:65], v[208:211], v[90:93], v[50:65]
	s_waitcnt lgkmcnt(9)
	v_mfma_f32_32x32x16_bf16 v[66:81], v[150:153], v[102:105], v[66:81]
	s_waitcnt lgkmcnt(8)
	v_mfma_f32_32x32x16_bf16 v[50:65], v[212:215], v[102:105], v[50:65]
	s_waitcnt lgkmcnt(7)
	v_mfma_f32_32x32x16_bf16 v[66:81], v[154:157], v[98:101], v[66:81]
	ds_read2_b64 v[154:157], v4 offset0:196 offset1:198
	ds_read2_b64 v[146:149], v4 offset0:200 offset1:202
	ds_read2_b64 v[8:11], v4 offset0:204 offset1:206
	v_add_u32_e32 v4, 0xa000, v187
	ds_read2_b64 v[158:161], v4 offset0:32 offset1:34
	ds_read2_b64 v[150:153], v4 offset0:36 offset1:38
	ds_read2_b64 v[12:15], v4 offset0:40 offset1:42
	ds_read2_b64 v[4:7], v4 offset0:44 offset1:46
	s_waitcnt lgkmcnt(13)
	v_mfma_f32_32x32x16_bf16 v[50:65], v[216:219], v[98:101], v[50:65]
	s_nop 1
	v_max3_f32 v16, v66, s38, v67
	v_max3_f32 v16, v16, v68, v69
	v_max3_f32 v16, v16, v70, v71
	v_max3_f32 v16, v16, v72, v73
	v_max3_f32 v16, v16, v74, v75
	v_max3_f32 v16, v16, v76, v77
	v_max3_f32 v16, v16, v78, v79
	v_max3_f32 v16, v16, v80, v81
	s_nop 1
	v_max3_f32 v16, v16, v50, v51
	v_max3_f32 v16, v16, v52, v53
	v_max3_f32 v16, v16, v54, v55
	v_max3_f32 v16, v16, v56, v57
	v_max3_f32 v16, v16, v58, v59
	v_max3_f32 v16, v16, v60, v61
	v_max3_f32 v16, v16, v62, v63
	v_max3_f32 v16, v16, v64, v65
	v_cmp_lt_f32_e32 vcc, s39, v16
	s_or_b64 vcc, s[0:1], vcc
	s_cbranch_vccz .LBB0_987
	v_mov_b32_e32 v17, v16
	s_nop 1
	v_permlane32_swap_b32_e32 v16, v17
	v_max_f32_e32 v17, v17, v17
	v_max_f32_e32 v16, v16, v16
	v_max_f32_e32 v16, v16, v17
	v_cmp_lt_f32_e32 vcc, s39, v16
	s_or_b64 vcc, s[0:1], vcc
	s_nop 0
	v_cndmask_b32_e32 v16, 0, v16, vcc
	v_exp_f32_e64 v17, -v16
	v_add_f32_e32 v2, v2, v16
	v_sub_f32_e32 v228, 0, v2
	v_mov_b32_e32 v229, v228
	v_mov_b32_e32 v230, v228
	v_mov_b32_e32 v231, v228
	v_mov_b32_e32 v232, v228
	v_mov_b32_e32 v233, v228
	v_mov_b32_e32 v234, v228
	v_mov_b32_e32 v235, v228
	v_mov_b32_e32 v236, v228
	v_mov_b32_e32 v237, v228
	v_mov_b32_e32 v238, v228
	v_mov_b32_e32 v239, v228
	v_mov_b32_e32 v240, v228
	v_mov_b32_e32 v241, v228
	v_mov_b32_e32 v242, v228
	v_mov_b32_e32 v243, v228
	v_cndmask_b32_e64 v204, v17, 1.0, s[0:1]
	v_mul_f32_e32 v177, v177, v204
	v_pk_add_f32 v[66:67], v[66:67], v[16:17] op_sel_hi:[1,0] neg_lo:[0,1] neg_hi:[0,1]
	v_pk_add_f32 v[68:69], v[68:69], v[16:17] op_sel_hi:[1,0] neg_lo:[0,1] neg_hi:[0,1]
	v_pk_add_f32 v[70:71], v[70:71], v[16:17] op_sel_hi:[1,0] neg_lo:[0,1] neg_hi:[0,1]
	v_pk_add_f32 v[72:73], v[72:73], v[16:17] op_sel_hi:[1,0] neg_lo:[0,1] neg_hi:[0,1]
	v_pk_add_f32 v[74:75], v[74:75], v[16:17] op_sel_hi:[1,0] neg_lo:[0,1] neg_hi:[0,1]
	v_pk_add_f32 v[76:77], v[76:77], v[16:17] op_sel_hi:[1,0] neg_lo:[0,1] neg_hi:[0,1]
	v_pk_add_f32 v[78:79], v[78:79], v[16:17] op_sel_hi:[1,0] neg_lo:[0,1] neg_hi:[0,1]
	v_pk_add_f32 v[80:81], v[80:81], v[16:17] op_sel_hi:[1,0] neg_lo:[0,1] neg_hi:[0,1]
	v_pk_add_f32 v[50:51], v[50:51], v[16:17] op_sel_hi:[1,0] neg_lo:[0,1] neg_hi:[0,1]
	v_pk_add_f32 v[52:53], v[52:53], v[16:17] op_sel_hi:[1,0] neg_lo:[0,1] neg_hi:[0,1]
	v_pk_add_f32 v[54:55], v[54:55], v[16:17] op_sel_hi:[1,0] neg_lo:[0,1] neg_hi:[0,1]
	v_pk_add_f32 v[56:57], v[56:57], v[16:17] op_sel_hi:[1,0] neg_lo:[0,1] neg_hi:[0,1]
	v_pk_add_f32 v[58:59], v[58:59], v[16:17] op_sel_hi:[1,0] neg_lo:[0,1] neg_hi:[0,1]
	v_pk_add_f32 v[60:61], v[60:61], v[16:17] op_sel_hi:[1,0] neg_lo:[0,1] neg_hi:[0,1]
	v_pk_add_f32 v[62:63], v[62:63], v[16:17] op_sel_hi:[1,0] neg_lo:[0,1] neg_hi:[0,1]
	v_pk_add_f32 v[64:65], v[64:65], v[16:17] op_sel_hi:[1,0] neg_lo:[0,1] neg_hi:[0,1]
	v_pk_mul_f32 v[48:49], v[48:49], v[204:205] op_sel_hi:[1,0]
	v_pk_mul_f32 v[46:47], v[46:47], v[204:205] op_sel_hi:[1,0]
	v_pk_mul_f32 v[44:45], v[44:45], v[204:205] op_sel_hi:[1,0]
	v_pk_mul_f32 v[42:43], v[42:43], v[204:205] op_sel_hi:[1,0]
	v_pk_mul_f32 v[40:41], v[40:41], v[204:205] op_sel_hi:[1,0]
	v_pk_mul_f32 v[38:39], v[38:39], v[204:205] op_sel_hi:[1,0]
	v_pk_mul_f32 v[36:37], v[36:37], v[204:205] op_sel_hi:[1,0]
	v_pk_mul_f32 v[34:35], v[34:35], v[204:205] op_sel_hi:[1,0]
	v_pk_mul_f32 v[32:33], v[32:33], v[204:205] op_sel_hi:[1,0]
	v_pk_mul_f32 v[30:31], v[30:31], v[204:205] op_sel_hi:[1,0]
	v_pk_mul_f32 v[28:29], v[28:29], v[204:205] op_sel_hi:[1,0]
	v_pk_mul_f32 v[26:27], v[26:27], v[204:205] op_sel_hi:[1,0]
	v_pk_mul_f32 v[24:25], v[24:25], v[204:205] op_sel_hi:[1,0]
	v_pk_mul_f32 v[22:23], v[22:23], v[204:205] op_sel_hi:[1,0]
	v_pk_mul_f32 v[20:21], v[20:21], v[204:205] op_sel_hi:[1,0]
	v_pk_mul_f32 v[18:19], v[18:19], v[204:205] op_sel_hi:[1,0]
	s_branch .LBB0_987

; template <int DQK, int MODE> ...
;     ...
;   auto lstore = [&](const TRegs& R, int st) {
;     u16* Ks = lds + st * STG;
;     u16* Vs = Ks + KT;
; #pragma unroll
;     for (int i = 0; i < NKL; ++i) {
;       int c = tid + i * 256;
;       int row = c / KCH, cc = c % KCH;
;       *(u32x4*)(Ks + row * KST + cc * 8) = R.k[i];
;     }
; #pragma unroll
;     for (int i = 0; i < 2; ++i) {
;       int c = tid + i * 256;
;       int d = c >> 3, cc = c & 7;
;       u32x2 lo = {R.v[i].x, R.v[i].y}, hi = {R.v[i].z, R.v[i].w};
;       *(u32x2*)(Vs + d * VST + cc * 8) = lo;
;       *(u32x2*)(Vs + d * VST + cc * 8 + 4) = hi;
;     }
;   };
;     ...
;       {
;         bf16x8 kf[2][NKK];
; #pragma unroll
;         for (int ku = 0; ku < 2; ++ku)
; #pragma unroll
;           for (int kk = 0; kk < NKK; ++kk)
;             kf[ku][kk] = *(const bf16x8*)(Ks + (ku * 32 + ql) * KST + kk * 16 + hh * 8);
;         __builtin_amdgcn_sched_barrier(0);
; #pragma unroll
;         for (int ku = 0; ku < 2; ++ku)
; #pragma unroll
;           for (int r = 0; r < 16; ++r) S[ku][r] = cinit;
; #pragma unroll
;         for (int kk = 0; kk < NKK; ++kk)
; #pragma unroll
;           for (int ku = 0; ku < 2; ++ku)
;             S[ku] = __builtin_amdgcn_mfma_f32_32x32x16_bf16(kf[ku][kk], qf[kk], S[ku], 0, 0, 0);
;       }
.LBB0_2129:
	s_and_saveexec_b64 s[14:15], s[30:31]
	s_cbranch_execz .Lmy_ia0_b
	ds_read_b128 v[2:5], v183
	ds_read_b128 v[156:159], v183 offset:6656
	ds_read_b128 v[6:9], v183 offset:32
	ds_read_b128 v[160:163], v183 offset:6688
	ds_read_b128 v[10:13], v183 offset:64
	ds_read_b128 v[204:207], v183 offset:6720
	ds_read_b128 v[144:147], v183 offset:96
	ds_read_b128 v[208:211], v183 offset:6752
	ds_read_b128 v[148:151], v183 offset:128
	ds_read_b128 v[212:215], v183 offset:6784
	ds_read_b128 v[152:155], v183 offset:160
	ds_read_b128 v[216:219], v183 offset:6816
	s_waitcnt lgkmcnt(11)
	v_mfma_f32_32x32x16_bf16 v[64:79], v[2:5], v[84:87], v[228:243]
	v_add_u32_e32 v2, 0x3000, v185
	s_waitcnt lgkmcnt(10)
	v_mfma_f32_32x32x16_bf16 v[48:63], v[156:159], v[84:87], v[228:243]
	s_waitcnt lgkmcnt(9)
	v_mfma_f32_32x32x16_bf16 v[64:79], v[6:9], v[80:83], v[64:79]
	s_waitcnt lgkmcnt(8)
	v_mfma_f32_32x32x16_bf16 v[48:63], v[160:163], v[80:83], v[48:63]
	ds_read2_b64 v[160:163], v2 offset0:128 offset1:130
	s_waitcnt lgkmcnt(8)
	v_mfma_f32_32x32x16_bf16 v[64:79], v[10:13], v[92:95], v[64:79]
	s_waitcnt lgkmcnt(7)
	v_mfma_f32_32x32x16_bf16 v[48:63], v[204:207], v[92:95], v[48:63]
	s_cmp_gt_i32 s18, s16
	s_cbranch_scc1 .Lmy_w5_nl
	v_add_u32_e32 v226, 0x8e00, v182
	s_waitcnt vmcnt(9)
	ds_write_b128 v200, v[120:123] offset:23040
	s_waitcnt vmcnt(8)
	ds_write_b128 v201, v[124:127] offset:23040
	s_waitcnt vmcnt(7)
	ds_write_b128 v202, v[132:135] offset:23040
	s_waitcnt vmcnt(6)
	ds_write2_b64 v226, v[136:137], v[138:139] offset1:1
	v_add_u32_e32 v226, 0x8e00, v184
	s_waitcnt vmcnt(5)
	ds_write2_b64 v226, v[140:141], v[142:143] offset1:1
	s_branch .Lmy_w5_dn

; template <int DQK, int MODE> ...
;     ...
;       {
;         bf16x8 kf[2][NKK];
; #pragma unroll
;         for (int ku = 0; ku < 2; ++ku)
; #pragma unroll
;           for (int kk = 0; kk < NKK; ++kk)
;             kf[ku][kk] = *(const bf16x8*)(Ks + (ku * 32 + ql) * KST + kk * 16 + hh * 8);
;         __builtin_amdgcn_sched_barrier(0);
; #pragma unroll
;         for (int ku = 0; ku < 2; ++ku)
; #pragma unroll
;           for (int r = 0; r < 16; ++r) S[ku][r] = cinit;
; #pragma unroll
;         for (int kk = 0; kk < NKK; ++kk)
; #pragma unroll
;           for (int ku = 0; ku < 2; ++ku)
;             S[ku] = __builtin_amdgcn_mfma_f32_32x32x16_bf16(kf[ku][kk], qf[kk], S[ku], 0, 0, 0);
;       }
;       u32x4 vf[2][4];
;       if (MODE != 2) {
; #pragma unroll
;         for (int du = 0; du < 2; ++du)
; #pragma unroll
;           for (int s4 = 0; s4 < 4; ++s4) {
;             const u16* vp = Vs + (du * 32 + ql) * VST + 16 * s4 + 4 * hh;
;             u32x2 a = *(const u32x2*)vp;
;             u32x2 b = *(const u32x2*)(vp + 8);
;             vf[du][s4] = (u32x4){a.x, a.y, b.x, b.y};
;           }
;         __builtin_amdgcn_sched_barrier(0);
;       }
;       bf16x8 pf[4];
;       if (MODE != 2) {
;         if (MODE == 1 && !far) {
;           const bool noclip = ((qpos0 + 32 * w + 31) - j * 64 <= 256) && ((qpos0 + 32 * w) - (j * 64 + 63) >= -256);
;           if (noclip) {
;             const float* bt = btab + 256 + qpos - j * 64;
; #pragma unroll
;             for (int ku = 0; ku < 2; ++ku)
; #pragma unroll
;               for (int r = 0; r < 16; ++r) S[ku][r] += bt[-(32 * ku + (r & 3) + 8 * (r >> 2) + 4 * hh)];
;           } else {
; #pragma unroll
;             for (int ku = 0; ku < 2; ++ku)
; #pragma unroll
;               for (int r = 0; r < 16; ++r) {
;                 int key = 32 * ku + (r & 3) + 8 * (r >> 2) + 4 * hh;
;                 int rel = qpos - (j * 64 + key);
;                 rel = min(256, max(-256, rel)) + 256;
;                 S[ku][r] += btab[rel];
;               }
;           }
;         }
;         float mx = -1e30f;
; #pragma unroll
;         for (int ku = 0; ku < 2; ++ku)
; #pragma unroll
;           for (int r = 0; r < 16; ++r) mx = fmaxf(mx, S[ku][r]);
;         if (__builtin_amdgcn_ballot_w64(first || mx > 6.f) != 0ull) {
;           mx = xhalf_max(mx);
;           const float d = first ? mx : (mx > 6.f ? mx : 0.f);
.Lmy_w5_dn:
	s_waitcnt lgkmcnt(11)
	v_mfma_f32_32x32x16_bf16 v[64:79], v[144:147], v[88:91], v[64:79]
	s_waitcnt lgkmcnt(10)
	v_mfma_f32_32x32x16_bf16 v[48:63], v[208:211], v[88:91], v[48:63]
	s_waitcnt lgkmcnt(9)
	v_mfma_f32_32x32x16_bf16 v[64:79], v[148:151], v[100:103], v[64:79]
	s_waitcnt lgkmcnt(8)
	v_mfma_f32_32x32x16_bf16 v[48:63], v[212:215], v[100:103], v[48:63]
	s_waitcnt lgkmcnt(7)
	v_mfma_f32_32x32x16_bf16 v[64:79], v[152:155], v[96:99], v[64:79]
	ds_read2_b64 v[152:155], v2 offset0:132 offset1:134
	ds_read2_b64 v[144:147], v2 offset0:136 offset1:138
	ds_read2_b64 v[6:9], v2 offset0:140 offset1:142
	v_add_u32_e32 v2, 0x4000, v185
	ds_read2_b64 v[156:159], v2 offset0:224 offset1:226
	ds_read2_b64 v[148:151], v2 offset0:228 offset1:230
	ds_read2_b64 v[10:13], v2 offset0:232 offset1:234
	ds_read2_b64 v[2:5], v2 offset0:236 offset1:238
	s_waitcnt lgkmcnt(13)
	v_mfma_f32_32x32x16_bf16 v[48:63], v[216:219], v[96:99], v[48:63]
	s_nop 1
	v_max3_f32 v14, v64, s96, v65
	v_max3_f32 v14, v14, v66, v67
	v_max3_f32 v14, v14, v68, v69
	v_max3_f32 v14, v14, v70, v71
	v_max3_f32 v14, v14, v72, v73
	v_max3_f32 v14, v14, v74, v75
	v_max3_f32 v14, v14, v76, v77
	v_max3_f32 v14, v14, v78, v79
	s_nop 1
	v_max3_f32 v14, v14, v48, v49
	v_max3_f32 v14, v14, v50, v51
	v_max3_f32 v14, v14, v52, v53
	v_max3_f32 v14, v14, v54, v55
	v_max3_f32 v14, v14, v56, v57
	v_max3_f32 v14, v14, v58, v59
	v_max3_f32 v14, v14, v60, v61
	v_max3_f32 v14, v14, v62, v63
	v_cmp_lt_f32_e32 vcc, s97, v14
	s_or_b64 vcc, s[10:11], vcc
	s_cbranch_vccz .LBB0_2132
	v_mov_b32_e32 v15, v14
	s_nop 1
	v_permlane32_swap_b32_e32 v14, v15
	v_max_f32_e32 v15, v15, v15
	v_max_f32_e32 v14, v14, v14
	v_max_f32_e32 v14, v14, v15
	v_cmp_lt_f32_e32 vcc, s97, v14
	s_or_b64 vcc, s[10:11], vcc
	s_nop 0
	v_cndmask_b32_e32 v14, 0, v14, vcc
	v_exp_f32_e64 v15, -v14
	v_add_f32_e32 v0, v0, v14
	v_sub_f32_e32 v228, 0, v0
	v_mov_b32_e32 v229, v228
	v_mov_b32_e32 v230, v228
	v_mov_b32_e32 v231, v228
	v_mov_b32_e32 v232, v228
	v_mov_b32_e32 v233, v228
	v_mov_b32_e32 v234, v228
	v_mov_b32_e32 v235, v228
	v_mov_b32_e32 v236, v228
	v_mov_b32_e32 v237, v228
	v_mov_b32_e32 v238, v228
	v_mov_b32_e32 v239, v228
	v_mov_b32_e32 v240, v228
	v_mov_b32_e32 v241, v228
	v_mov_b32_e32 v242, v228
	v_mov_b32_e32 v243, v228
	v_cndmask_b32_e64 v204, v15, 1.0, s[10:11]
	v_mul_f32_e32 v175, v175, v204
	v_pk_add_f32 v[64:65], v[64:65], v[14:15] op_sel_hi:[1,0] neg_lo:[0,1] neg_hi:[0,1]
	v_pk_add_f32 v[66:67], v[66:67], v[14:15] op_sel_hi:[1,0] neg_lo:[0,1] neg_hi:[0,1]
	v_pk_add_f32 v[68:69], v[68:69], v[14:15] op_sel_hi:[1,0] neg_lo:[0,1] neg_hi:[0,1]
	v_pk_add_f32 v[70:71], v[70:71], v[14:15] op_sel_hi:[1,0] neg_lo:[0,1] neg_hi:[0,1]
	v_pk_add_f32 v[72:73], v[72:73], v[14:15] op_sel_hi:[1,0] neg_lo:[0,1] neg_hi:[0,1]
	v_pk_add_f32 v[74:75], v[74:75], v[14:15] op_sel_hi:[1,0] neg_lo:[0,1] neg_hi:[0,1]
	v_pk_add_f32 v[76:77], v[76:77], v[14:15] op_sel_hi:[1,0] neg_lo:[0,1] neg_hi:[0,1]
	v_pk_add_f32 v[78:79], v[78:79], v[14:15] op_sel_hi:[1,0] neg_lo:[0,1] neg_hi:[0,1]
	v_pk_add_f32 v[48:49], v[48:49], v[14:15] op_sel_hi:[1,0] neg_lo:[0,1] neg_hi:[0,1]
	v_pk_add_f32 v[50:51], v[50:51], v[14:15] op_sel_hi:[1,0] neg_lo:[0,1] neg_hi:[0,1]
	v_pk_add_f32 v[52:53], v[52:53], v[14:15] op_sel_hi:[1,0] neg_lo:[0,1] neg_hi:[0,1]
	v_pk_add_f32 v[54:55], v[54:55], v[14:15] op_sel_hi:[1,0] neg_lo:[0,1] neg_hi:[0,1]
	v_pk_add_f32 v[56:57], v[56:57], v[14:15] op_sel_hi:[1,0] neg_lo:[0,1] neg_hi:[0,1]
	v_pk_add_f32 v[58:59], v[58:59], v[14:15] op_sel_hi:[1,0] neg_lo:[0,1] neg_hi:[0,1]
	v_pk_add_f32 v[60:61], v[60:61], v[14:15] op_sel_hi:[1,0] neg_lo:[0,1] neg_hi:[0,1]
	v_pk_add_f32 v[62:63], v[62:63], v[14:15] op_sel_hi:[1,0] neg_lo:[0,1] neg_hi:[0,1]
	v_pk_mul_f32 v[46:47], v[46:47], v[204:205] op_sel_hi:[1,0]
	v_pk_mul_f32 v[44:45], v[44:45], v[204:205] op_sel_hi:[1,0]
	v_pk_mul_f32 v[42:43], v[42:43], v[204:205] op_sel_hi:[1,0]
	v_pk_mul_f32 v[40:41], v[40:41], v[204:205] op_sel_hi:[1,0]
	v_pk_mul_f32 v[38:39], v[38:39], v[204:205] op_sel_hi:[1,0]
	v_pk_mul_f32 v[36:37], v[36:37], v[204:205] op_sel_hi:[1,0]
	v_pk_mul_f32 v[34:35], v[34:35], v[204:205] op_sel_hi:[1,0]
	v_pk_mul_f32 v[32:33], v[32:33], v[204:205] op_sel_hi:[1,0]
	v_pk_mul_f32 v[30:31], v[30:31], v[204:205] op_sel_hi:[1,0]
	v_pk_mul_f32 v[28:29], v[28:29], v[204:205] op_sel_hi:[1,0]
	v_pk_mul_f32 v[26:27], v[26:27], v[204:205] op_sel_hi:[1,0]
	v_pk_mul_f32 v[24:25], v[24:25], v[204:205] op_sel_hi:[1,0]
	v_pk_mul_f32 v[22:23], v[22:23], v[204:205] op_sel_hi:[1,0]
	v_pk_mul_f32 v[20:21], v[20:21], v[204:205] op_sel_hi:[1,0]
	v_pk_mul_f32 v[18:19], v[18:19], v[204:205] op_sel_hi:[1,0]
	v_pk_mul_f32 v[16:17], v[16:17], v[204:205] op_sel_hi:[1,0]

; template <int DQK, int MODE> ...
;     ...
;   auto lstore = [&](const TRegs& R, int st) {
;     u16* Ks = lds + st * STG;
;     u16* Vs = Ks + KT;
; #pragma unroll
;     for (int i = 0; i < NKL; ++i) {
;       int c = tid + i * 256;
;       int row = c / KCH, cc = c % KCH;
;       *(u32x4*)(Ks + row * KST + cc * 8) = R.k[i];
;     }
; #pragma unroll
;     for (int i = 0; i < 2; ++i) {
;       int c = tid + i * 256;
;       int d = c >> 3, cc = c & 7;
;       u32x2 lo = {R.v[i].x, R.v[i].y}, hi = {R.v[i].z, R.v[i].w};
;       *(u32x2*)(Vs + d * VST + cc * 8) = lo;
;       *(u32x2*)(Vs + d * VST + cc * 8 + 4) = hi;
;     }
;     ...
; #pragma unroll
;         for (int ku = 0; ku < 2; ++ku)
; #pragma unroll
;           for (int kk = 0; kk < NKK; ++kk)
;             kf[ku][kk] = *(const bf16x8*)(Ks + (ku * 32 + ql) * KST + kk * 16 + hh * 8);
;         __builtin_amdgcn_sched_barrier(0);
; #pragma unroll
;         for (int ku = 0; ku < 2; ++ku)
; #pragma unroll
;           for (int r = 0; r < 16; ++r) S[ku][r] = cinit;
; #pragma unroll
;         for (int kk = 0; kk < NKK; ++kk)
; #pragma unroll
;           for (int ku = 0; ku < 2; ++ku)
;             S[ku] = __builtin_amdgcn_mfma_f32_32x32x16_bf16(kf[ku][kk], qf[kk], S[ku], 0, 0, 0);
.LBB0_2136:
	s_and_saveexec_b64 s[14:15], s[30:31]
	s_cbranch_execz .Lmy_ia1_b
	ds_read_b128 v[2:5], v183 offset:23040
	ds_read_b128 v[156:159], v183 offset:29696
	ds_read_b128 v[6:9], v183 offset:23072
	ds_read_b128 v[160:163], v183 offset:29728
	ds_read_b128 v[10:13], v183 offset:23104
	ds_read_b128 v[204:207], v183 offset:29760
	ds_read_b128 v[144:147], v183 offset:23136
	ds_read_b128 v[208:211], v183 offset:29792
	ds_read_b128 v[148:151], v183 offset:23168
	ds_read_b128 v[212:215], v183 offset:29824
	ds_read_b128 v[152:155], v183 offset:23200
	ds_read_b128 v[216:219], v183 offset:29856
	s_waitcnt lgkmcnt(11)
	v_mfma_f32_32x32x16_bf16 v[64:79], v[2:5], v[84:87], v[228:243]
	v_add_u32_e32 v2, 0x8800, v185
	s_waitcnt lgkmcnt(10)
	v_mfma_f32_32x32x16_bf16 v[48:63], v[156:159], v[84:87], v[228:243]
	s_waitcnt lgkmcnt(9)
	v_mfma_f32_32x32x16_bf16 v[64:79], v[6:9], v[80:83], v[64:79]
	s_waitcnt lgkmcnt(8)
	v_mfma_f32_32x32x16_bf16 v[48:63], v[160:163], v[80:83], v[48:63]
	ds_read2_b64 v[160:163], v2 offset0:192 offset1:194
	s_waitcnt lgkmcnt(8)
	v_mfma_f32_32x32x16_bf16 v[64:79], v[10:13], v[92:95], v[64:79]
	s_waitcnt lgkmcnt(7)
	v_mfma_f32_32x32x16_bf16 v[48:63], v[204:207], v[92:95], v[48:63]
	s_cmp_gt_i32 s17, s16
	s_cbranch_scc1 .Lmy_w6_nl
	v_add_u32_e32 v226, 0x3400, v182
	s_waitcnt vmcnt(9)
	ds_write_b128 v200, v[104:107]
	s_waitcnt vmcnt(8)
	ds_write_b128 v201, v[108:111]
	s_waitcnt vmcnt(7)
	ds_write_b128 v202, v[112:115]
	s_waitcnt vmcnt(6)
	ds_write2_b64 v226, v[116:117], v[118:119] offset1:1
	v_add_u32_e32 v226, 0x3400, v184
	s_waitcnt vmcnt(5)
	ds_write2_b64 v226, v[128:129], v[130:131] offset1:1
	s_branch .Lmy_w6_dn

; template <int DQK, int MODE> ...
;     ...
;       {
;         bf16x8 kf[2][NKK];
; #pragma unroll
;         for (int ku = 0; ku < 2; ++ku)
; #pragma unroll
;           for (int kk = 0; kk < NKK; ++kk)
;             kf[ku][kk] = *(const bf16x8*)(Ks + (ku * 32 + ql) * KST + kk * 16 + hh * 8);
;         __builtin_amdgcn_sched_barrier(0);
; #pragma unroll
;         for (int ku = 0; ku < 2; ++ku)
; #pragma unroll
;           for (int r = 0; r < 16; ++r) S[ku][r] = cinit;
; #pragma unroll
;         for (int kk = 0; kk < NKK; ++kk)
; #pragma unroll
;           for (int ku = 0; ku < 2; ++ku)
;             S[ku] = __builtin_amdgcn_mfma_f32_32x32x16_bf16(kf[ku][kk], qf[kk], S[ku], 0, 0, 0);
;       }
;       u32x4 vf[2][4];
;       if (MODE != 2) {
; #pragma unroll
;         for (int du = 0; du < 2; ++du)
; #pragma unroll
;           for (int s4 = 0; s4 < 4; ++s4) {
;             const u16* vp = Vs + (du * 32 + ql) * VST + 16 * s4 + 4 * hh;
;             u32x2 a = *(const u32x2*)vp;
;             u32x2 b = *(const u32x2*)(vp + 8);
;             vf[du][s4] = (u32x4){a.x, a.y, b.x, b.y};
;           }
;         __builtin_amdgcn_sched_barrier(0);
;       }
;       bf16x8 pf[4];
;       if (MODE != 2) {
;         if (MODE == 1 && !far) {
;           const bool noclip = ((qpos0 + 32 * w + 31) - j * 64 <= 256) && ((qpos0 + 32 * w) - (j * 64 + 63) >= -256);
;           if (noclip) {
;             const float* bt = btab + 256 + qpos - j * 64;
; #pragma unroll
;             for (int ku = 0; ku < 2; ++ku)
; #pragma unroll
;               for (int r = 0; r < 16; ++r) S[ku][r] += bt[-(32 * ku + (r & 3) + 8 * (r >> 2) + 4 * hh)];
;           } else {
; #pragma unroll
;             for (int ku = 0; ku < 2; ++ku)
; #pragma unroll
;               for (int r = 0; r < 16; ++r) {
;                 int key = 32 * ku + (r & 3) + 8 * (r >> 2) + 4 * hh;
;                 int rel = qpos - (j * 64 + key);
;                 rel = min(256, max(-256, rel)) + 256;
;                 S[ku][r] += btab[rel];
;               }
;           }
;         }
;         float mx = -1e30f;
; #pragma unroll
;         for (int ku = 0; ku < 2; ++ku)
; #pragma unroll
;           for (int r = 0; r < 16; ++r) mx = fmaxf(mx, S[ku][r]);
;         if (__builtin_amdgcn_ballot_w64(first || mx > 6.f) != 0ull) {
;           mx = xhalf_max(mx);
;           const float d = first ? mx : (mx > 6.f ? mx : 0.f);
.Lmy_w6_dn:
	s_waitcnt lgkmcnt(11)
	v_mfma_f32_32x32x16_bf16 v[64:79], v[144:147], v[88:91], v[64:79]
	s_waitcnt lgkmcnt(10)
	v_mfma_f32_32x32x16_bf16 v[48:63], v[208:211], v[88:91], v[48:63]
	s_waitcnt lgkmcnt(9)
	v_mfma_f32_32x32x16_bf16 v[64:79], v[148:151], v[100:103], v[64:79]
	s_waitcnt lgkmcnt(8)
	v_mfma_f32_32x32x16_bf16 v[48:63], v[212:215], v[100:103], v[48:63]
	s_waitcnt lgkmcnt(7)
	v_mfma_f32_32x32x16_bf16 v[64:79], v[152:155], v[96:99], v[64:79]
	ds_read2_b64 v[152:155], v2 offset0:196 offset1:198
	ds_read2_b64 v[144:147], v2 offset0:200 offset1:202
	ds_read2_b64 v[6:9], v2 offset0:204 offset1:206
	v_add_u32_e32 v2, 0xa000, v185
	ds_read2_b64 v[156:159], v2 offset0:32 offset1:34
	ds_read2_b64 v[148:151], v2 offset0:36 offset1:38
	ds_read2_b64 v[10:13], v2 offset0:40 offset1:42
	ds_read2_b64 v[2:5], v2 offset0:44 offset1:46
	s_waitcnt lgkmcnt(13)
	v_mfma_f32_32x32x16_bf16 v[48:63], v[216:219], v[96:99], v[48:63]
	s_nop 1
	v_max3_f32 v14, v64, s96, v65
	v_max3_f32 v14, v14, v66, v67
	v_max3_f32 v14, v14, v68, v69
	v_max3_f32 v14, v14, v70, v71
	v_max3_f32 v14, v14, v72, v73
	v_max3_f32 v14, v14, v74, v75
	v_max3_f32 v14, v14, v76, v77
	v_max3_f32 v14, v14, v78, v79
	s_nop 1
	v_max3_f32 v14, v14, v48, v49
	v_max3_f32 v14, v14, v50, v51
	v_max3_f32 v14, v14, v52, v53
	v_max3_f32 v14, v14, v54, v55
	v_max3_f32 v14, v14, v56, v57
	v_max3_f32 v14, v14, v58, v59
	v_max3_f32 v14, v14, v60, v61
	v_max3_f32 v14, v14, v62, v63
	v_cmp_lt_f32_e32 vcc, s97, v14
	s_or_b64 vcc, s[10:11], vcc
	s_cbranch_vccz .LBB0_2124
	v_mov_b32_e32 v15, v14
	s_nop 1
	v_permlane32_swap_b32_e32 v14, v15
	v_max_f32_e32 v15, v15, v15
	v_max_f32_e32 v14, v14, v14
	v_max_f32_e32 v14, v14, v15
	v_cmp_lt_f32_e32 vcc, s97, v14
	s_or_b64 vcc, s[10:11], vcc
	s_nop 0
	v_cndmask_b32_e32 v14, 0, v14, vcc
	v_exp_f32_e64 v15, -v14
	v_add_f32_e32 v0, v0, v14
	v_sub_f32_e32 v228, 0, v0
	v_mov_b32_e32 v229, v228
	v_mov_b32_e32 v230, v228
	v_mov_b32_e32 v231, v228
	v_mov_b32_e32 v232, v228
	v_mov_b32_e32 v233, v228
	v_mov_b32_e32 v234, v228
	v_mov_b32_e32 v235, v228
	v_mov_b32_e32 v236, v228
	v_mov_b32_e32 v237, v228
	v_mov_b32_e32 v238, v228
	v_mov_b32_e32 v239, v228
	v_mov_b32_e32 v240, v228
	v_mov_b32_e32 v241, v228
	v_mov_b32_e32 v242, v228
	v_mov_b32_e32 v243, v228
	v_cndmask_b32_e64 v204, v15, 1.0, s[10:11]
	v_mul_f32_e32 v175, v175, v204
	v_pk_add_f32 v[64:65], v[64:65], v[14:15] op_sel_hi:[1,0] neg_lo:[0,1] neg_hi:[0,1]
	v_pk_add_f32 v[66:67], v[66:67], v[14:15] op_sel_hi:[1,0] neg_lo:[0,1] neg_hi:[0,1]
	v_pk_add_f32 v[68:69], v[68:69], v[14:15] op_sel_hi:[1,0] neg_lo:[0,1] neg_hi:[0,1]
	v_pk_add_f32 v[70:71], v[70:71], v[14:15] op_sel_hi:[1,0] neg_lo:[0,1] neg_hi:[0,1]
	v_pk_add_f32 v[72:73], v[72:73], v[14:15] op_sel_hi:[1,0] neg_lo:[0,1] neg_hi:[0,1]
	v_pk_add_f32 v[74:75], v[74:75], v[14:15] op_sel_hi:[1,0] neg_lo:[0,1] neg_hi:[0,1]
	v_pk_add_f32 v[76:77], v[76:77], v[14:15] op_sel_hi:[1,0] neg_lo:[0,1] neg_hi:[0,1]
	v_pk_add_f32 v[78:79], v[78:79], v[14:15] op_sel_hi:[1,0] neg_lo:[0,1] neg_hi:[0,1]
	v_pk_add_f32 v[48:49], v[48:49], v[14:15] op_sel_hi:[1,0] neg_lo:[0,1] neg_hi:[0,1]
	v_pk_add_f32 v[50:51], v[50:51], v[14:15] op_sel_hi:[1,0] neg_lo:[0,1] neg_hi:[0,1]
	v_pk_add_f32 v[52:53], v[52:53], v[14:15] op_sel_hi:[1,0] neg_lo:[0,1] neg_hi:[0,1]
	v_pk_add_f32 v[54:55], v[54:55], v[14:15] op_sel_hi:[1,0] neg_lo:[0,1] neg_hi:[0,1]
	v_pk_add_f32 v[56:57], v[56:57], v[14:15] op_sel_hi:[1,0] neg_lo:[0,1] neg_hi:[0,1]
	v_pk_add_f32 v[58:59], v[58:59], v[14:15] op_sel_hi:[1,0] neg_lo:[0,1] neg_hi:[0,1]
	v_pk_add_f32 v[60:61], v[60:61], v[14:15] op_sel_hi:[1,0] neg_lo:[0,1] neg_hi:[0,1]
	v_pk_add_f32 v[62:63], v[62:63], v[14:15] op_sel_hi:[1,0] neg_lo:[0,1] neg_hi:[0,1]
	v_pk_mul_f32 v[46:47], v[46:47], v[204:205] op_sel_hi:[1,0]
	v_pk_mul_f32 v[44:45], v[44:45], v[204:205] op_sel_hi:[1,0]
	v_pk_mul_f32 v[42:43], v[42:43], v[204:205] op_sel_hi:[1,0]
	v_pk_mul_f32 v[40:41], v[40:41], v[204:205] op_sel_hi:[1,0]
	v_pk_mul_f32 v[38:39], v[38:39], v[204:205] op_sel_hi:[1,0]
	v_pk_mul_f32 v[36:37], v[36:37], v[204:205] op_sel_hi:[1,0]
	v_pk_mul_f32 v[34:35], v[34:35], v[204:205] op_sel_hi:[1,0]
	v_pk_mul_f32 v[32:33], v[32:33], v[204:205] op_sel_hi:[1,0]
	v_pk_mul_f32 v[30:31], v[30:31], v[204:205] op_sel_hi:[1,0]
	v_pk_mul_f32 v[28:29], v[28:29], v[204:205] op_sel_hi:[1,0]
	v_pk_mul_f32 v[26:27], v[26:27], v[204:205] op_sel_hi:[1,0]
	v_pk_mul_f32 v[24:25], v[24:25], v[204:205] op_sel_hi:[1,0]
	v_pk_mul_f32 v[22:23], v[22:23], v[204:205] op_sel_hi:[1,0]
	v_pk_mul_f32 v[20:21], v[20:21], v[204:205] op_sel_hi:[1,0]
	v_pk_mul_f32 v[18:19], v[18:19], v[204:205] op_sel_hi:[1,0]
	v_pk_mul_f32 v[16:17], v[16:17], v[204:205] op_sel_hi:[1,0]
	s_branch .LBB0_2124
